# token_c: the two 8-lane sum-of-squares reductions via DPP (quad_perm, row_half_mirror) instead of three ds_bpermute round trips each, same pairing order; on top of the rmsnorm DPP version
# baseline (speedup 1.0000x reference)
; DI unsigned pk2(float a, float b) { f32x2 v = {a, b}; return __builtin_bit_cast(unsigned, __builtin_convertvector(v, bf16x2)); }
; DI float bf2f(unsigned short u) { return __uint_as_float(((unsigned)u) << 16); }
; DI void phase_token_c(const Params& P, int layer, char* smem) {
;     ...
;       ss += __shfl_xor(ss, 1); ss += __shfl_xor(ss, 2); ss += __shfl_xor(ss, 4);
;       const float r = rsqrtf(ss * (1.f / 96) + EPS);
;       unsigned o[6];
; #pragma unroll
;       for (int e = 0; e < 6; ++e) o[e] = pk2(f[2 * e] * r * gq[j0 + 2 * e], f[2 * e + 1] * r * gq[j0 + 2 * e + 1]);
;       u32x2* op = (u32x2*)(qr + lane * 12);
;       op[0] = u32x2{o[0], o[1]}; op[1] = u32x2{o[2], o[3]}; op[2] = u32x2{o[4], o[5]};
;     }
;     {
;       float f[12];
;       float ss = 0.f;
;       const int hd = lane >> 3, j0 = (lane & 7) * 12;
; #pragma unroll
;       for (int e = 0; e < 12; ++e) {
;         const int j = j0 + e;
;         const float v = (j < 64) ? bf2f(KV[(size_t)t * 1024 + hd * 128 + j]) : bf2f(Z[(size_t)t * ZLD + C_KR + (j - 64)]);
;         f[e] = v; ss += v * v;
;       }
;       ss += __shfl_xor(ss, 1); ss += __shfl_xor(ss, 2); ss += __shfl_xor(ss, 4);
;       const float r = rsqrtf(ss * (1.f / 96) + EPS);
;       unsigned o[6];
; #pragma unroll
;       for (int e = 0; e < 6; ++e) o[e] = pk2(f[2 * e] * r * gk[j0 + 2 * e], f[2 * e + 1] * r * gk[j0 + 2 * e + 1]);
;       u32x2* op = (u32x2*)(KB + ((size_t)((t / S_) * 8 + hd) * S_ + (t % S_)) * 96 + j0);
;       op[0] = u32x2{o[0], o[1]}; op[1] = u32x2{o[2], o[3]}; op[2] = u32x2{o[4], o[5]};
;     }
;     __syncthreads();
.LBB0_189:
	s_or_b64 exec, exec, s[0:1]
	s_waitcnt lgkmcnt(0)
	v_mul_f32_e32 v59, v19, v19
	v_fmac_f32_e32 v59, v18, v18
	v_fmac_f32_e32 v59, v2, v2
	v_fmac_f32_e32 v59, v3, v3
	v_fmac_f32_e32 v59, v20, v20
	v_fmac_f32_e32 v59, v21, v21
	v_fmac_f32_e32 v59, v22, v22
	v_fmac_f32_e32 v59, v23, v23
	v_fmac_f32_e32 v59, v24, v24
	v_fmac_f32_e32 v59, v25, v25
	v_fmac_f32_e32 v59, v26, v26
	v_fmac_f32_e32 v59, v27, v27
	s_mov_b32 s3, 0x800000
	s_add_i32 s2, s2, s70
	s_cmpk_gt_i32 s2, 0x1fff
	s_waitcnt lgkmcnt(0)
	s_nop 1
	v_add_f32_dpp v59, v59, v59 quad_perm:[1,0,3,2] row_mask:0xf bank_mask:0xf
	s_nop 1
	v_add_f32_dpp v59, v59, v59 quad_perm:[2,3,0,1] row_mask:0xf bank_mask:0xf
	s_nop 1
	v_add_f32_dpp v59, v59, v59 row_half_mirror row_mask:0xf bank_mask:0xf
	v_fmamk_f32 v59, v59, 0x3c2aaaab, v165
	v_cmp_gt_f32_e64 s[0:1], s3, v59
	v_mul_f32_e32 v60, 0x4b800000, v59
	s_nop 0
	v_cndmask_b32_e64 v59, v59, v60, s[0:1]
	v_rsq_f32_e32 v59, v59
	s_nop 0
	v_mul_f32_e32 v60, 0x45800000, v59
	v_cndmask_b32_e64 v72, v59, v60, s[0:1]
	v_mul_f32_e32 v72, 0x3e16c740, v72
	global_load_dwordx4 v[60:63], v[8:9], off offset:32
	global_load_dwordx4 v[64:67], v[8:9], off offset:16
	global_load_dwordx4 v[68:71], v[8:9], off
	v_pk_mul_f32 v[18:19], v[18:19], v[72:73] op_sel_hi:[1,0]
	v_pk_mul_f32 v[2:3], v[2:3], v[72:73] op_sel_hi:[1,0]
	s_waitcnt vmcnt(0)
	v_pk_mul_f32 v[18:19], v[68:69], v[18:19]
	v_pk_mul_f32 v[2:3], v[70:71], v[2:3]
	v_cvt_pk_bf16_f32 v18, v18, v19
	v_cvt_pk_bf16_f32 v19, v2, v3
	v_pk_mul_f32 v[2:3], v[20:21], v[72:73] op_sel_hi:[1,0]
	s_nop 0
	v_pk_mul_f32 v[2:3], v[64:65], v[2:3]
	s_nop 0
	v_cvt_pk_bf16_f32 v20, v2, v3
	v_pk_mul_f32 v[2:3], v[22:23], v[72:73] op_sel_hi:[1,0]
	v_pk_mul_f32 v[22:23], v[26:27], v[72:73] op_sel_hi:[1,0]
	v_pk_mul_f32 v[2:3], v[66:67], v[2:3]
	v_pk_mul_f32 v[22:23], v[22:23], v[62:63]
	v_cvt_pk_bf16_f32 v21, v2, v3
	v_pk_mul_f32 v[2:3], v[24:25], v[72:73] op_sel_hi:[1,0]
	s_nop 0
	v_pk_mul_f32 v[2:3], v[60:61], v[2:3]
	s_nop 0
	v_cvt_pk_bf16_f32 v2, v2, v3
	v_cvt_pk_bf16_f32 v3, v22, v23
	v_lshlrev_b32_e32 v22, 1, v4
	v_mov_b32_e32 v23, v137
	v_lshl_add_u64 v[0:1], v[0:1], 0, v[22:23]
	global_store_dwordx4 v[0:1], v[18:21], off
	global_store_dwordx2 v[0:1], v[2:3], off offset:16
	v_mad_i64_i32 v[2:3], s[0:1], v16, s33, v[14:15]
	v_lshlrev_b64 v[0:1], 11, v[16:17]
	s_mov_b64 s[0:1], 0xa001510
	v_lshl_add_u64 v[0:1], v[12:13], 0, v[0:1]
	v_lshl_add_u64 v[18:19], v[2:3], 0, s[0:1]
	v_cndmask_b32_e64 v19, v19, v1, s[40:41]
	v_cndmask_b32_e64 v18, v18, v0, s[40:41]
	global_load_dwordx2 v[26:27], v[18:19], off
	s_mov_b64 s[0:1], 0xa001518
	v_lshl_add_u64 v[0:1], v[0:1], 0, 8
	v_lshl_add_u64 v[2:3], v[2:3], 0, s[0:1]
	v_cndmask_b32_e64 v1, v3, v1, s[46:47]
	v_cndmask_b32_e64 v0, v2, v0, s[46:47]
	global_load_dwordx4 v[0:3], v[0:1], off
	s_nop 0
	global_load_dwordx4 v[18:21], v[10:11], off offset:32
	global_load_dwordx4 v[22:25], v[10:11], off offset:16
	global_load_dwordx4 v[60:63], v[10:11], off
	s_waitcnt vmcnt(4)
	v_and_b32_e32 v77, 0xffff0000, v27
	v_lshlrev_b32_e32 v76, 16, v27
	v_and_b32_e32 v27, 0xffff0000, v26
	v_lshlrev_b32_e32 v26, 16, v26
	v_pk_mul_f32 v[80:81], v[26:27], v[26:27]
	v_pk_mul_f32 v[78:79], v[76:77], v[76:77]
	v_add_f32_e32 v17, v80, v81
	s_waitcnt vmcnt(3)
	v_and_b32_e32 v75, 0xffff0000, v0
	v_lshlrev_b32_e32 v74, 16, v0
	v_add_f32_e32 v17, v17, v78
	v_and_b32_e32 v71, 0xffff0000, v1
	v_lshlrev_b32_e32 v70, 16, v1
	v_pk_mul_f32 v[0:1], v[74:75], v[74:75]
	v_add_f32_e32 v17, v17, v79
	v_add_f32_e32 v0, v17, v0
	v_pk_mul_f32 v[72:73], v[70:71], v[70:71]
	v_add_f32_e32 v0, v0, v1
	v_and_b32_e32 v69, 0xffff0000, v2
	v_lshlrev_b32_e32 v68, 16, v2
	v_add_f32_e32 v0, v0, v72
	v_and_b32_e32 v65, 0xffff0000, v3
	v_lshlrev_b32_e32 v64, 16, v3
	v_pk_mul_f32 v[2:3], v[68:69], v[68:69]
	v_add_f32_e32 v0, v0, v73
	v_add_f32_e32 v0, v0, v2
	v_pk_mul_f32 v[66:67], v[64:65], v[64:65]
	v_add_f32_e32 v0, v0, v3
	v_add_f32_e32 v0, v0, v66
	v_add_f32_e32 v0, v0, v67
	v_ashrrev_i32_e32 v17, 31, v16
	v_lshrrev_b32_e32 v17, 18, v17
	v_add_u32_e32 v17, v16, v17
	v_ashrrev_i32_e32 v17, 14, v17
	s_waitcnt lgkmcnt(0)
	s_nop 1
	v_add_f32_dpp v0, v0, v0 quad_perm:[1,0,3,2] row_mask:0xf bank_mask:0xf
	s_nop 1
	v_add_f32_dpp v0, v0, v0 quad_perm:[2,3,0,1] row_mask:0xf bank_mask:0xf
	s_nop 1
	v_add_f32_dpp v0, v0, v0 row_half_mirror row_mask:0xf bank_mask:0xf
	v_fmamk_f32 v0, v0, 0x3c2aaaab, v165
	v_cmp_gt_f32_e64 s[0:1], s3, v0
	v_mul_f32_e32 v1, 0x4b800000, v0
	s_nop 0
	v_cndmask_b32_e64 v0, v0, v1, s[0:1]
	v_rsq_f32_e32 v0, v0
	s_nop 0
	v_mul_f32_e32 v1, 0x45800000, v0
	v_cndmask_b32_e64 v66, v0, v1, s[0:1]
	v_pk_mul_f32 v[0:1], v[66:67], v[26:27] op_sel_hi:[0,1]
	v_pk_mul_f32 v[2:3], v[66:67], v[76:77] op_sel_hi:[0,1]
	s_waitcnt vmcnt(0)
	v_pk_mul_f32 v[0:1], v[60:61], v[0:1]
	v_pk_mul_f32 v[2:3], v[62:63], v[2:3]
	v_cvt_pk_bf16_f32 v0, v0, v1
	v_cvt_pk_bf16_f32 v1, v2, v3
	v_pk_mul_f32 v[2:3], v[66:67], v[74:75] op_sel_hi:[0,1]
	v_pk_mul_f32 v[2:3], v[22:23], v[2:3]
	v_pk_mul_f32 v[22:23], v[66:67], v[70:71] op_sel_hi:[0,1]
	v_pk_mul_f32 v[22:23], v[24:25], v[22:23]
	v_cvt_pk_bf16_f32 v2, v2, v3
	v_cvt_pk_bf16_f32 v3, v22, v23
	v_pk_mul_f32 v[22:23], v[66:67], v[68:69] op_sel_hi:[0,1]
	v_pk_mul_f32 v[18:19], v[18:19], v[22:23]
	v_pk_mul_f32 v[22:23], v[66:67], v[64:65] op_sel_hi:[0,1]
	v_pk_mul_f32 v[20:21], v[20:21], v[22:23]
	v_cvt_pk_bf16_f32 v18, v18, v19
	v_cvt_pk_bf16_f32 v19, v20, v21
	v_lshl_or_b32 v20, v17, 3, v29
	v_mul_i32_i24_e32 v17, 0x4000, v17
	v_ashrrev_i32_e32 v21, 31, v20
	v_sub_u32_e32 v22, v16, v17
	v_lshlrev_b64 v[20:21], 14, v[20:21]
	v_ashrrev_i32_e32 v23, 31, v22
	v_lshl_add_u64 v[20:21], v[20:21], 0, v[22:23]
	v_mad_u64_u32 v[22:23], s[0:1], v20, s72, v[6:7]
	v_mad_i32_i24 v23, v21, s72, v23
	v_add_u32_e32 v16, s26, v16
	global_store_dwordx4 v[22:23], v[0:3], off
	global_store_dwordx2 v[22:23], v[18:19], off offset:16
	s_barrier
	s_cbranch_scc1 .LBB0_244
